# v20 + gate-GEMM epilogue: 8-byte rho stores of adjacent branches paired across 16-lane rows (v_permlane16_swap) into dwordx4 stores
# speedup vs baseline: 1.0268x; 1.0037x over previous
; DI float gate_clamped(float x) { return fmaxf(__builtin_amdgcn_rcpf(1.f + __expf(-x)), 6.103515625e-05f); }
;   DI void operator()(const f4 (&acc)[2][2][4][2], const GUnit& u, int wr, int wc, int fr, int fq) const {
;     char* rb = (char*)(gb + (size_t)((u.pm - pm0) * 256 + wr * 64) * 4096 + u.pn * 64 + wc * 16);
;     const unsigned lo = (unsigned)(fr * 4096 + 4 * fq) * 2u;
; #pragma unroll
;     for (int ai = 0; ai < 2; ++ai)
; #pragma unroll
;       for (int m = 0; m < 4; ++m) {
;         f4 gq[4];
; #pragma unroll
;         for (int br = 0; br < 4; ++br)
; #pragma unroll
;           for (int j = 0; j < 4; ++j) gq[br][j] = gate_clamped(acc[ai][br >> 1][m][br & 1][j]);
; #pragma unroll
;         for (int br = 0; br < 4; ++br) {
;           h4 o;
; #pragma unroll
;           for (int j = 0; j < 4; ++j) o[j] = (half_t)(br < 3 ? gq[br][j] * __builtin_amdgcn_rcpf(gq[br + 1][j]) : gq[3][j]);
;           *(h4*)(rb + ((size_t)(ai * 128 + m * 16) * 4096 + br * 1024) * 2 + lo) = o;
;         }
;       }
.LBB0_2268:
	v_mbcnt_lo_u32_b32 v248, -1, 0
	v_mbcnt_hi_u32_b32 v248, -1, v248
	v_bfe_u32 v248, v248, 4, 1
	v_mul_u32_u24_e32 v248, 0x7f8, v248
	v_mov_b32_e32 v249, 0
	v_mul_f32_e32 v116, 0xbfb8aa3b, v116
	v_exp_f32_e32 v116, v116
	v_mul_f32_e32 v117, 0xbfb8aa3b, v117
	v_mul_f32_e32 v115, 0xbfb8aa3b, v115
	v_exp_f32_e32 v117, v117
	v_exp_f32_e32 v115, v115
	v_add_f32_e32 v116, 1.0, v116
	v_rcp_f32_e32 v147, v116
	v_add_f32_e32 v116, 1.0, v117
	v_add_f32_e32 v115, 1.0, v115
	v_rcp_f32_e32 v148, v116
	v_mul_f32_e32 v116, 0xbfb8aa3b, v126
	v_rcp_f32_e32 v115, v115
	v_exp_f32_e32 v126, v116
	v_mul_f32_e32 v122, 0xbfb8aa3b, v122
	v_mul_f32_e32 v123, 0xbfb8aa3b, v123
	v_max_f32_e32 v116, 0x38800000, v115
	v_add_f32_e32 v115, 1.0, v126
	v_mul_f32_e32 v126, 0xbfb8aa3b, v127
	v_mul_f32_e32 v127, 0xbfb8aa3b, v128
	v_mul_f32_e32 v128, 0xbfb8aa3b, v129
	v_exp_f32_e32 v122, v122
	v_exp_f32_e32 v123, v123
	v_rcp_f32_e32 v115, v115
	v_exp_f32_e32 v128, v128
	v_add_f32_e32 v122, 1.0, v122
	v_add_f32_e32 v123, 1.0, v123
	v_max_f32_e32 v129, 0x38800000, v115
	v_add_f32_e32 v115, 1.0, v128
	v_rcp_f32_e32 v122, v122
	v_rcp_f32_e32 v123, v123
	v_mul_f32_e32 v124, 0xbfb8aa3b, v124
	v_rcp_f32_e32 v115, v115
	v_exp_f32_e32 v124, v124
	v_max_f32_e32 v117, 0x38800000, v147
	v_max_f32_e32 v147, 0x38800000, v148
	v_max_f32_e32 v148, 0x38800000, v122
	v_max_f32_e32 v122, 0x38800000, v123
	v_mul_f32_e32 v123, 0xbfb8aa3b, v125
	v_exp_f32_e32 v126, v126
	v_exp_f32_e32 v127, v127
	v_max_f32_e32 v128, 0x38800000, v115
	v_add_f32_e32 v115, 1.0, v124
	v_exp_f32_e32 v123, v123
	v_mul_f32_e32 v119, 0xbfb8aa3b, v119
	v_rcp_f32_e32 v115, v115
	v_exp_f32_e32 v119, v119
	v_mul_f32_e32 v114, 0xbfb8aa3b, v114
	v_add_f32_e32 v126, 1.0, v126
	v_add_f32_e32 v127, 1.0, v127
	v_add_f32_e32 v123, 1.0, v123
	v_exp_f32_e32 v114, v114
	v_rcp_f32_e32 v126, v126
	v_rcp_f32_e32 v127, v127
	v_rcp_f32_e32 v124, v123
	v_max_f32_e32 v123, 0x38800000, v115
	v_add_f32_e32 v115, 1.0, v119
	v_rcp_f32_e32 v115, v115
	v_add_f32_e32 v114, 1.0, v114
	s_sub_i32 s5, s84, s90
	v_max_f32_e32 v126, 0x38800000, v126
	v_max_f32_e32 v127, 0x38800000, v127
	v_rcp_f32_e32 v125, v114
	s_lshl_b32 s5, s5, 8
	v_mul_f32_e32 v119, 0xbfb8aa3b, v120
	v_mul_f32_e32 v120, 0xbfb8aa3b, v121
	v_max_f32_e32 v121, 0x38800000, v115
	v_rcp_f32_e32 v149, v129
	v_rcp_f32_e32 v114, v126
	v_rcp_f32_e32 v115, v127
	s_add_i32 s12, s5, s27
	s_ashr_i32 s13, s12, 31
	s_lshl_b64 s[12:13], s[12:13], 13
	v_max_f32_e32 v125, 0x38800000, v125
	s_add_u32 s5, s76, s12
	v_fma_mixlo_f16 v125, v125, v149, 0
	v_rcp_f32_e32 v149, v128
	v_pk_mul_f32 v[114:115], v[116:117], v[114:115]
	s_addc_u32 s14, s77, s13
	s_lshl_b32 s12, s10, 6
	v_mul_f32_e32 v118, 0xbfb8aa3b, v118
	v_exp_f32_e32 v119, v119
	v_cvt_pk_f16_f32 v115, v114, v115
	s_ashr_i32 s13, s12, 31
	v_exp_f32_e32 v118, v118
	v_exp_f32_e32 v120, v120
	v_pack_b32_f16 v114, v125, v115
	v_rcp_f32_e32 v125, v148
	s_lshl_b64 s[12:13], s[12:13], 1
	s_add_u32 s5, s5, s12
	v_fma_mixlo_f16 v116, v147, v149, 0
	s_addc_u32 s10, s14, s13
	v_max_f32_e32 v124, 0x38800000, v124
	v_add_f32_e32 v119, 1.0, v119
	v_alignbit_b32 v115, v116, v115, 16
	v_rcp_f32_e32 v116, v122
	v_rcp_f32_e32 v117, v123
	s_add_u32 s12, s5, s61
	v_add_f32_e32 v118, 1.0, v118
	v_rcp_f32_e32 v119, v119
	v_add_f32_e32 v120, 1.0, v120
	v_fma_mixlo_f16 v125, v125, v129, 0
	v_rcp_f32_e32 v129, v124
	s_addc_u32 s13, s10, 0
	v_rcp_f32_e32 v118, v118
	v_rcp_f32_e32 v120, v120
	v_lshl_add_u64 v[144:145], s[12:13], 0, v[138:139]
	v_mov_b32_e32 v218, v114
	v_mov_b32_e32 v219, v115
	v_pk_mul_f32 v[114:115], v[116:117], v[126:127]
	v_max_f32_e32 v119, 0x38800000, v119
	v_cvt_pk_f16_f32 v115, v114, v115
	v_fma_mixlo_f16 v116, v129, v128, 0
	v_max_f32_e32 v118, 0x38800000, v118
	v_max_f32_e32 v120, 0x38800000, v120
	v_pack_b32_f16 v114, v125, v115
	v_alignbit_b32 v115, v116, v115, 16
	v_rcp_f32_e32 v116, v121
	v_rcp_f32_e32 v117, v119
	v_rcp_f32_e32 v125, v118
	v_rcp_f32_e32 v126, v120
	v_mul_f32_e32 v100, 0xbfb8aa3b, v100
	v_mov_b32_e32 v220, v114
	v_mov_b32_e32 v221, v115
	s_nop 1
	v_permlane16_swap_b32_e32 v218, v220
	v_permlane16_swap_b32_e32 v219, v221
	v_lshl_add_u64 v[250:251], v[144:145], 0, v[248:249]
	global_store_dwordx4 v[250:251], v[218:221], off
	v_pk_mul_f32 v[114:115], v[122:123], v[116:117]
	v_exp_f32_e32 v100, v100
	v_mul_f32_e32 v101, 0xbfb8aa3b, v101
	v_fma_mixlo_f16 v125, v148, v125, 0
	v_cvt_pk_f16_f32 v115, v114, v115
	v_fma_mixlo_f16 v116, v124, v126, 0
	s_movk_i32 s5, 0x1000
	v_mul_f32_e32 v99, 0xbfb8aa3b, v99
	v_exp_f32_e32 v101, v101
	v_pack_b32_f16 v114, v125, v115
	v_alignbit_b32 v115, v116, v115, 16
	v_add_co_u32_e32 v116, vcc, s5, v144
	v_exp_f32_e32 v99, v99
	s_nop 0
	v_addc_co_u32_e32 v117, vcc, 0, v145, vcc
	v_mov_b32_e32 v218, v114
	v_mov_b32_e32 v219, v115
	v_cvt_pk_f16_f32 v115, v119, v120
	v_cvt_pk_f16_f32 v114, v118, v121
	v_add_f32_e32 v100, 1.0, v100
	v_mov_b32_e32 v220, v114
	v_mov_b32_e32 v221, v115
	s_nop 1
	v_permlane16_swap_b32_e32 v218, v220
	v_permlane16_swap_b32_e32 v219, v221
	v_lshl_add_u64 v[250:251], v[116:117], 0, v[248:249]
	global_store_dwordx4 v[250:251], v[218:221], off
	v_rcp_f32_e32 v114, v100
	v_add_f32_e32 v100, 1.0, v101
	v_add_f32_e32 v99, 1.0, v99
	v_rcp_f32_e32 v115, v100
	v_mul_f32_e32 v100, 0xbfb8aa3b, v110
	v_rcp_f32_e32 v99, v99
	v_exp_f32_e32 v110, v100
	v_mul_f32_e32 v106, 0xbfb8aa3b, v106
	v_mul_f32_e32 v107, 0xbfb8aa3b, v107
	v_max_f32_e32 v100, 0x38800000, v99
	v_add_f32_e32 v99, 1.0, v110
	v_mul_f32_e32 v110, 0xbfb8aa3b, v111
	v_mul_f32_e32 v111, 0xbfb8aa3b, v112
	v_mul_f32_e32 v112, 0xbfb8aa3b, v113
	v_exp_f32_e32 v106, v106
	v_exp_f32_e32 v107, v107
	v_rcp_f32_e32 v99, v99
; DI float gate_clamped(float x) { return fmaxf(__builtin_amdgcn_rcpf(1.f + __expf(-x)), 6.103515625e-05f); }
;   DI void operator()(const f4 (&acc)[2][2][4][2], const GUnit& u, int wr, int wc, int fr, int fq) const {
;     char* rb = (char*)(gb + (size_t)((u.pm - pm0) * 256 + wr * 64) * 4096 + u.pn * 64 + wc * 16);
;     const unsigned lo = (unsigned)(fr * 4096 + 4 * fq) * 2u;
; #pragma unroll
;     for (int ai = 0; ai < 2; ++ai)
; #pragma unroll
;       for (int m = 0; m < 4; ++m) {
;         f4 gq[4];
; #pragma unroll
;         for (int br = 0; br < 4; ++br)
; #pragma unroll
;           for (int j = 0; j < 4; ++j) gq[br][j] = gate_clamped(acc[ai][br >> 1][m][br & 1][j]);
; #pragma unroll
;         for (int br = 0; br < 4; ++br) {
;           h4 o;
; #pragma unroll
;           for (int j = 0; j < 4; ++j) o[j] = (half_t)(br < 3 ? gq[br][j] * __builtin_amdgcn_rcpf(gq[br + 1][j]) : gq[3][j]);
;           *(h4*)(rb + ((size_t)(ai * 128 + m * 16) * 4096 + br * 1024) * 2 + lo) = o;
;         }
;       }
	v_exp_f32_e32 v112, v112
	v_add_f32_e32 v106, 1.0, v106
	v_add_f32_e32 v107, 1.0, v107
	v_mul_f32_e32 v102, 0xbfb8aa3b, v102
	v_max_f32_e32 v113, 0x38800000, v99
	v_add_f32_e32 v99, 1.0, v112
	v_rcp_f32_e32 v106, v106
	v_rcp_f32_e32 v107, v107
	v_mul_f32_e32 v108, 0xbfb8aa3b, v108
	v_exp_f32_e32 v102, v102
	v_rcp_f32_e32 v99, v99
	v_exp_f32_e32 v108, v108
	v_max_f32_e32 v101, 0x38800000, v114
	v_max_f32_e32 v114, 0x38800000, v115
	v_max_f32_e32 v115, 0x38800000, v106
	v_max_f32_e32 v106, 0x38800000, v107
	v_mul_f32_e32 v107, 0xbfb8aa3b, v109
	v_add_f32_e32 v102, 1.0, v102
	v_max_f32_e32 v112, 0x38800000, v99
	v_add_f32_e32 v99, 1.0, v108
	v_exp_f32_e32 v107, v107
	v_rcp_f32_e32 v102, v102
	v_mul_f32_e32 v103, 0xbfb8aa3b, v103
	v_rcp_f32_e32 v99, v99
	v_exp_f32_e32 v103, v103
	v_add_f32_e32 v107, 1.0, v107
	v_max_f32_e32 v109, 0x38800000, v102
	v_mul_f32_e32 v102, 0xbfb8aa3b, v104
	v_rcp_f32_e32 v108, v107
	v_max_f32_e32 v107, 0x38800000, v99
	v_add_f32_e32 v99, 1.0, v103
	v_exp_f32_e32 v102, v102
	v_mul_f32_e32 v103, 0xbfb8aa3b, v105
	v_exp_f32_e32 v103, v103
	v_mul_f32_e32 v98, 0xbfb8aa3b, v98
	v_exp_f32_e32 v110, v110
	v_exp_f32_e32 v111, v111
	v_add_f32_e32 v102, 1.0, v102
	v_exp_f32_e32 v98, v98
	v_rcp_f32_e32 v102, v102
	v_add_f32_e32 v103, 1.0, v103
	v_rcp_f32_e32 v103, v103
	v_add_f32_e32 v110, 1.0, v110
	v_add_f32_e32 v111, 1.0, v111
	v_add_f32_e32 v98, 1.0, v98
	v_rcp_f32_e32 v110, v110
	v_rcp_f32_e32 v111, v111
	v_max_f32_e32 v117, 0x38800000, v102
	v_rcp_f32_e32 v102, v98
	v_rcp_f32_e32 v99, v99
	v_max_f32_e32 v118, 0x38800000, v103
	v_rcp_f32_e32 v103, v113
	v_max_f32_e32 v110, 0x38800000, v110
	v_max_f32_e32 v111, 0x38800000, v111
	v_max_f32_e32 v102, 0x38800000, v102
	v_max_f32_e32 v116, 0x38800000, v99
	v_rcp_f32_e32 v98, v110
	v_rcp_f32_e32 v99, v111
	v_fma_mixlo_f16 v102, v102, v103, 0
	v_rcp_f32_e32 v103, v112
	v_max_f32_e32 v108, 0x38800000, v108
	v_pk_mul_f32 v[98:99], v[100:101], v[98:99]
	v_rcp_f32_e32 v104, v106
	v_fma_mixlo_f16 v100, v114, v103, 0
	v_rcp_f32_e32 v114, v115
	v_cvt_pk_f16_f32 v99, v98, v99
	v_pack_b32_f16 v98, v102, v99
	v_alignbit_b32 v99, v100, v99, 16
	v_add_co_u32_e32 v100, vcc, s51, v144
	v_rcp_f32_e32 v105, v107
	s_nop 0
	v_addc_co_u32_e32 v101, vcc, 0, v145, vcc
	s_mov_b32 s5, 0x21000
	v_fma_mixlo_f16 v113, v114, v113, 0
	v_rcp_f32_e32 v114, v108
	v_add_co_u32_e32 v102, vcc, s5, v144
	v_mul_f32_e32 v84, 0xbfb8aa3b, v84
	s_nop 0
	v_addc_co_u32_e32 v103, vcc, 0, v145, vcc
	v_mov_b32_e32 v218, v98
	v_mov_b32_e32 v219, v99
	v_pk_mul_f32 v[98:99], v[104:105], v[110:111]
	v_fma_mixlo_f16 v104, v114, v112, 0
	v_cvt_pk_f16_f32 v99, v98, v99
	v_pack_b32_f16 v98, v113, v99
	v_alignbit_b32 v99, v104, v99, 16
	v_rcp_f32_e32 v104, v116
	v_rcp_f32_e32 v105, v117
	v_rcp_f32_e32 v110, v109
	v_mov_b32_e32 v220, v98
	v_mov_b32_e32 v221, v99
	s_nop 1
	v_permlane16_swap_b32_e32 v218, v220
	v_permlane16_swap_b32_e32 v219, v221
	v_lshl_add_u64 v[250:251], v[102:103], 0, v[248:249]
	global_store_dwordx4 v[250:251], v[218:221], off offset:-4096
	v_rcp_f32_e32 v101, v118
	v_pk_mul_f32 v[98:99], v[106:107], v[104:105]
	v_exp_f32_e32 v84, v84
	v_mul_f32_e32 v85, 0xbfb8aa3b, v85
	v_fma_mixlo_f16 v100, v115, v110, 0
	v_cvt_pk_f16_f32 v99, v98, v99
	v_mul_f32_e32 v83, 0xbfb8aa3b, v83
	v_exp_f32_e32 v85, v85
	v_pack_b32_f16 v98, v100, v99
	v_fma_mixlo_f16 v100, v108, v101, 0
	v_exp_f32_e32 v83, v83
	v_alignbit_b32 v99, v100, v99, 16
	v_mov_b32_e32 v218, v98
	v_mov_b32_e32 v219, v99
	v_cvt_pk_f16_f32 v99, v117, v118
	v_cvt_pk_f16_f32 v98, v109, v116
	v_add_f32_e32 v84, 1.0, v84
	v_mov_b32_e32 v220, v98
	v_mov_b32_e32 v221, v99
	s_nop 1
	v_permlane16_swap_b32_e32 v218, v220
	v_permlane16_swap_b32_e32 v219, v221
	v_lshl_add_u64 v[250:251], v[102:103], 0, v[248:249]
	global_store_dwordx4 v[250:251], v[218:221], off
	v_rcp_f32_e32 v98, v84
	v_add_f32_e32 v84, 1.0, v85
	v_add_f32_e32 v83, 1.0, v83
	v_rcp_f32_e32 v99, v84
	v_mul_f32_e32 v84, 0xbfb8aa3b, v94
	v_rcp_f32_e32 v83, v83
	v_exp_f32_e32 v94, v84
	v_mul_f32_e32 v90, 0xbfb8aa3b, v90
	v_mul_f32_e32 v91, 0xbfb8aa3b, v91
	v_max_f32_e32 v84, 0x38800000, v83
	v_add_f32_e32 v83, 1.0, v94
	v_mul_f32_e32 v94, 0xbfb8aa3b, v95
	v_mul_f32_e32 v95, 0xbfb8aa3b, v96
	v_mul_f32_e32 v96, 0xbfb8aa3b, v97
	v_exp_f32_e32 v90, v90
	v_exp_f32_e32 v91, v91
	v_rcp_f32_e32 v83, v83
	v_exp_f32_e32 v96, v96
	v_add_f32_e32 v90, 1.0, v90
	v_add_f32_e32 v91, 1.0, v91
	v_mul_f32_e32 v86, 0xbfb8aa3b, v86
	v_max_f32_e32 v97, 0x38800000, v83
	v_add_f32_e32 v83, 1.0, v96
	v_rcp_f32_e32 v90, v90
	v_rcp_f32_e32 v91, v91
	v_mul_f32_e32 v92, 0xbfb8aa3b, v92
	v_exp_f32_e32 v86, v86
	v_rcp_f32_e32 v83, v83
	v_exp_f32_e32 v92, v92
	v_max_f32_e32 v85, 0x38800000, v98
	v_max_f32_e32 v98, 0x38800000, v99
	v_max_f32_e32 v99, 0x38800000, v90
	v_max_f32_e32 v90, 0x38800000, v91
	v_mul_f32_e32 v91, 0xbfb8aa3b, v93
	v_add_f32_e32 v86, 1.0, v86
	v_max_f32_e32 v96, 0x38800000, v83
	v_add_f32_e32 v83, 1.0, v92
	v_exp_f32_e32 v91, v91
	v_rcp_f32_e32 v86, v86
	v_mul_f32_e32 v87, 0xbfb8aa3b, v87
	v_rcp_f32_e32 v83, v83
	v_exp_f32_e32 v87, v87
	v_add_f32_e32 v91, 1.0, v91
	v_max_f32_e32 v93, 0x38800000, v86
	v_mul_f32_e32 v86, 0xbfb8aa3b, v88
	v_rcp_f32_e32 v92, v91
	v_max_f32_e32 v91, 0x38800000, v83
	v_add_f32_e32 v83, 1.0, v87
	v_exp_f32_e32 v86, v86
	v_mul_f32_e32 v87, 0xbfb8aa3b, v89
	v_exp_f32_e32 v87, v87
	v_mul_f32_e32 v82, 0xbfb8aa3b, v82
	v_exp_f32_e32 v94, v94
	v_exp_f32_e32 v95, v95
	v_add_f32_e32 v86, 1.0, v86
	v_exp_f32_e32 v82, v82
	v_rcp_f32_e32 v86, v86
	v_add_f32_e32 v87, 1.0, v87
	v_rcp_f32_e32 v87, v87
	v_add_f32_e32 v94, 1.0, v94
	v_add_f32_e32 v95, 1.0, v95
	v_add_f32_e32 v82, 1.0, v82
	v_rcp_f32_e32 v94, v94
; DI float gate_clamped(float x) { return fmaxf(__builtin_amdgcn_rcpf(1.f + __expf(-x)), 6.103515625e-05f); }
;   DI void operator()(const f4 (&acc)[2][2][4][2], const GUnit& u, int wr, int wc, int fr, int fq) const {
;     char* rb = (char*)(gb + (size_t)((u.pm - pm0) * 256 + wr * 64) * 4096 + u.pn * 64 + wc * 16);
;     const unsigned lo = (unsigned)(fr * 4096 + 4 * fq) * 2u;
; #pragma unroll
;     for (int ai = 0; ai < 2; ++ai)
; #pragma unroll
;       for (int m = 0; m < 4; ++m) {
;         f4 gq[4];
; #pragma unroll
;         for (int br = 0; br < 4; ++br)
; #pragma unroll
;           for (int j = 0; j < 4; ++j) gq[br][j] = gate_clamped(acc[ai][br >> 1][m][br & 1][j]);
; #pragma unroll
;         for (int br = 0; br < 4; ++br) {
;           h4 o;
; #pragma unroll
;           for (int j = 0; j < 4; ++j) o[j] = (half_t)(br < 3 ? gq[br][j] * __builtin_amdgcn_rcpf(gq[br + 1][j]) : gq[3][j]);
;           *(h4*)(rb + ((size_t)(ai * 128 + m * 16) * 4096 + br * 1024) * 2 + lo) = o;
;         }
;       }
	v_rcp_f32_e32 v95, v95
	v_max_f32_e32 v101, 0x38800000, v86
	v_rcp_f32_e32 v86, v82
	v_rcp_f32_e32 v83, v83
	v_max_f32_e32 v102, 0x38800000, v87
	v_rcp_f32_e32 v87, v97
	v_max_f32_e32 v94, 0x38800000, v94
	v_max_f32_e32 v95, 0x38800000, v95
	v_max_f32_e32 v86, 0x38800000, v86
	v_max_f32_e32 v100, 0x38800000, v83
	v_rcp_f32_e32 v82, v94
	v_rcp_f32_e32 v83, v95
	v_fma_mixlo_f16 v86, v86, v87, 0
	v_rcp_f32_e32 v87, v96
	v_max_f32_e32 v92, 0x38800000, v92
	v_pk_mul_f32 v[82:83], v[84:85], v[82:83]
	v_rcp_f32_e32 v88, v90
	v_fma_mixlo_f16 v84, v98, v87, 0
	v_rcp_f32_e32 v98, v99
	v_cvt_pk_f16_f32 v83, v82, v83
	v_pack_b32_f16 v82, v86, v83
	v_alignbit_b32 v83, v84, v83, 16
	v_add_co_u32_e32 v84, vcc, s47, v144
	v_rcp_f32_e32 v89, v91
	s_nop 0
	v_addc_co_u32_e32 v85, vcc, 0, v145, vcc
	s_mov_b32 s5, 0x41000
	v_fma_mixlo_f16 v97, v98, v97, 0
	v_rcp_f32_e32 v98, v92
	v_add_co_u32_e32 v86, vcc, s5, v144
	v_mul_f32_e32 v68, 0xbfb8aa3b, v68
	s_nop 0
	v_addc_co_u32_e32 v87, vcc, 0, v145, vcc
	v_mov_b32_e32 v218, v82
	v_mov_b32_e32 v219, v83
	v_pk_mul_f32 v[82:83], v[88:89], v[94:95]
	v_fma_mixlo_f16 v88, v98, v96, 0
	v_cvt_pk_f16_f32 v83, v82, v83
	v_pack_b32_f16 v82, v97, v83
	v_alignbit_b32 v83, v88, v83, 16
	v_rcp_f32_e32 v88, v100
	v_rcp_f32_e32 v89, v101
	v_rcp_f32_e32 v94, v93
	v_mov_b32_e32 v220, v82
	v_mov_b32_e32 v221, v83
	s_nop 1
	v_permlane16_swap_b32_e32 v218, v220
	v_permlane16_swap_b32_e32 v219, v221
	v_lshl_add_u64 v[250:251], v[86:87], 0, v[248:249]
	global_store_dwordx4 v[250:251], v[218:221], off offset:-4096
	v_rcp_f32_e32 v85, v102
	v_pk_mul_f32 v[82:83], v[90:91], v[88:89]
	v_exp_f32_e32 v68, v68
	v_mul_f32_e32 v69, 0xbfb8aa3b, v69
	v_fma_mixlo_f16 v84, v99, v94, 0
	v_cvt_pk_f16_f32 v83, v82, v83
	v_mul_f32_e32 v67, 0xbfb8aa3b, v67
	v_exp_f32_e32 v69, v69
	v_pack_b32_f16 v82, v84, v83
	v_fma_mixlo_f16 v84, v92, v85, 0
	v_exp_f32_e32 v67, v67
	v_alignbit_b32 v83, v84, v83, 16
	v_mov_b32_e32 v218, v82
	v_mov_b32_e32 v219, v83
	v_cvt_pk_f16_f32 v83, v101, v102
	v_cvt_pk_f16_f32 v82, v93, v100
	v_add_f32_e32 v68, 1.0, v68
	v_mov_b32_e32 v220, v82
	v_mov_b32_e32 v221, v83
	s_nop 1
	v_permlane16_swap_b32_e32 v218, v220
	v_permlane16_swap_b32_e32 v219, v221
	v_lshl_add_u64 v[250:251], v[86:87], 0, v[248:249]
	global_store_dwordx4 v[250:251], v[218:221], off
	v_rcp_f32_e32 v82, v68
	v_add_f32_e32 v68, 1.0, v69
	v_add_f32_e32 v67, 1.0, v67
	v_rcp_f32_e32 v83, v68
	v_mul_f32_e32 v68, 0xbfb8aa3b, v78
	v_rcp_f32_e32 v67, v67
	v_exp_f32_e32 v78, v68
	v_mul_f32_e32 v74, 0xbfb8aa3b, v74
	v_mul_f32_e32 v75, 0xbfb8aa3b, v75
	v_max_f32_e32 v68, 0x38800000, v67
	v_add_f32_e32 v67, 1.0, v78
	v_mul_f32_e32 v78, 0xbfb8aa3b, v79
	v_mul_f32_e32 v79, 0xbfb8aa3b, v80
	v_mul_f32_e32 v80, 0xbfb8aa3b, v81
	v_exp_f32_e32 v74, v74
	v_exp_f32_e32 v75, v75
	v_rcp_f32_e32 v67, v67
	v_exp_f32_e32 v80, v80
	v_add_f32_e32 v74, 1.0, v74
	v_add_f32_e32 v75, 1.0, v75
	v_mul_f32_e32 v70, 0xbfb8aa3b, v70
	v_max_f32_e32 v81, 0x38800000, v67
	v_add_f32_e32 v67, 1.0, v80
	v_rcp_f32_e32 v74, v74
	v_rcp_f32_e32 v75, v75
	v_mul_f32_e32 v76, 0xbfb8aa3b, v76
	v_exp_f32_e32 v70, v70
	v_rcp_f32_e32 v67, v67
	v_exp_f32_e32 v76, v76
	v_max_f32_e32 v69, 0x38800000, v82
	v_max_f32_e32 v82, 0x38800000, v83
	v_max_f32_e32 v83, 0x38800000, v74
	v_max_f32_e32 v74, 0x38800000, v75
	v_mul_f32_e32 v75, 0xbfb8aa3b, v77
	v_add_f32_e32 v70, 1.0, v70
	v_max_f32_e32 v80, 0x38800000, v67
	v_add_f32_e32 v67, 1.0, v76
	v_exp_f32_e32 v75, v75
	v_rcp_f32_e32 v70, v70
	v_mul_f32_e32 v71, 0xbfb8aa3b, v71
	v_rcp_f32_e32 v67, v67
	v_exp_f32_e32 v71, v71
	v_add_f32_e32 v75, 1.0, v75
	v_max_f32_e32 v77, 0x38800000, v70
	v_mul_f32_e32 v70, 0xbfb8aa3b, v72
	v_rcp_f32_e32 v76, v75
	v_max_f32_e32 v75, 0x38800000, v67
	v_add_f32_e32 v67, 1.0, v71
	v_exp_f32_e32 v70, v70
	v_mul_f32_e32 v71, 0xbfb8aa3b, v73
	v_exp_f32_e32 v71, v71
	v_mul_f32_e32 v66, 0xbfb8aa3b, v66
	v_exp_f32_e32 v78, v78
	v_exp_f32_e32 v79, v79
	v_add_f32_e32 v70, 1.0, v70
	v_exp_f32_e32 v66, v66
	v_rcp_f32_e32 v70, v70
	v_add_f32_e32 v71, 1.0, v71
	v_rcp_f32_e32 v71, v71
	v_add_f32_e32 v78, 1.0, v78
	v_add_f32_e32 v79, 1.0, v79
	v_add_f32_e32 v66, 1.0, v66
	v_rcp_f32_e32 v78, v78
	v_rcp_f32_e32 v79, v79
	v_max_f32_e32 v85, 0x38800000, v70
	v_rcp_f32_e32 v70, v66
	v_rcp_f32_e32 v67, v67
	v_max_f32_e32 v86, 0x38800000, v71
	v_rcp_f32_e32 v71, v81
	v_max_f32_e32 v78, 0x38800000, v78
	v_max_f32_e32 v79, 0x38800000, v79
	v_max_f32_e32 v70, 0x38800000, v70
	v_max_f32_e32 v84, 0x38800000, v67
	v_rcp_f32_e32 v66, v78
	v_rcp_f32_e32 v67, v79
	v_fma_mixlo_f16 v70, v70, v71, 0
	v_rcp_f32_e32 v71, v80
	v_max_f32_e32 v76, 0x38800000, v76
	v_pk_mul_f32 v[66:67], v[68:69], v[66:67]
	v_rcp_f32_e32 v72, v74
	v_fma_mixlo_f16 v68, v82, v71, 0
	v_rcp_f32_e32 v82, v83
	v_cvt_pk_f16_f32 v67, v66, v67
	v_pack_b32_f16 v66, v70, v67
	v_alignbit_b32 v67, v68, v67, 16
	v_add_co_u32_e32 v68, vcc, s72, v144
	v_rcp_f32_e32 v73, v75
	s_nop 0
	v_addc_co_u32_e32 v69, vcc, 0, v145, vcc
	s_mov_b32 s5, 0x61000
	v_fma_mixlo_f16 v81, v82, v81, 0
	v_rcp_f32_e32 v82, v76
	v_add_co_u32_e32 v70, vcc, s5, v144
	v_mul_f32_e32 v52, 0xbfb8aa3b, v52
	s_nop 0
	v_addc_co_u32_e32 v71, vcc, 0, v145, vcc
	v_mov_b32_e32 v218, v66
	v_mov_b32_e32 v219, v67
	v_pk_mul_f32 v[66:67], v[72:73], v[78:79]
	v_fma_mixlo_f16 v72, v82, v80, 0
	v_cvt_pk_f16_f32 v67, v66, v67
	v_pack_b32_f16 v66, v81, v67
	v_alignbit_b32 v67, v72, v67, 16
	v_rcp_f32_e32 v72, v84
	v_rcp_f32_e32 v73, v85
	v_rcp_f32_e32 v78, v77
	v_mov_b32_e32 v220, v66
	v_mov_b32_e32 v221, v67
	s_nop 1
	v_permlane16_swap_b32_e32 v218, v220
	v_permlane16_swap_b32_e32 v219, v221
	v_lshl_add_u64 v[250:251], v[70:71], 0, v[248:249]
; DI float gate_clamped(float x) { return fmaxf(__builtin_amdgcn_rcpf(1.f + __expf(-x)), 6.103515625e-05f); }
;   DI void operator()(const f4 (&acc)[2][2][4][2], const GUnit& u, int wr, int wc, int fr, int fq) const {
;     char* rb = (char*)(gb + (size_t)((u.pm - pm0) * 256 + wr * 64) * 4096 + u.pn * 64 + wc * 16);
;     const unsigned lo = (unsigned)(fr * 4096 + 4 * fq) * 2u;
; #pragma unroll
;     for (int ai = 0; ai < 2; ++ai)
; #pragma unroll
;       for (int m = 0; m < 4; ++m) {
;         f4 gq[4];
; #pragma unroll
;         for (int br = 0; br < 4; ++br)
; #pragma unroll
;           for (int j = 0; j < 4; ++j) gq[br][j] = gate_clamped(acc[ai][br >> 1][m][br & 1][j]);
; #pragma unroll
;         for (int br = 0; br < 4; ++br) {
;           h4 o;
; #pragma unroll
;           for (int j = 0; j < 4; ++j) o[j] = (half_t)(br < 3 ? gq[br][j] * __builtin_amdgcn_rcpf(gq[br + 1][j]) : gq[3][j]);
;           *(h4*)(rb + ((size_t)(ai * 128 + m * 16) * 4096 + br * 1024) * 2 + lo) = o;
;         }
;       }
	global_store_dwordx4 v[250:251], v[218:221], off offset:-4096
	v_rcp_f32_e32 v69, v86
	v_pk_mul_f32 v[66:67], v[74:75], v[72:73]
	v_exp_f32_e32 v52, v52
	v_mul_f32_e32 v53, 0xbfb8aa3b, v53
	v_fma_mixlo_f16 v68, v83, v78, 0
	v_cvt_pk_f16_f32 v67, v66, v67
	v_mul_f32_e32 v51, 0xbfb8aa3b, v51
	v_exp_f32_e32 v53, v53
	v_pack_b32_f16 v66, v68, v67
	v_fma_mixlo_f16 v68, v76, v69, 0
	v_exp_f32_e32 v51, v51
	v_alignbit_b32 v67, v68, v67, 16
	v_mov_b32_e32 v218, v66
	v_mov_b32_e32 v219, v67
	v_cvt_pk_f16_f32 v67, v85, v86
	v_cvt_pk_f16_f32 v66, v77, v84
	v_add_f32_e32 v52, 1.0, v52
	v_mov_b32_e32 v220, v66
	v_mov_b32_e32 v221, v67
	s_nop 1
	v_permlane16_swap_b32_e32 v218, v220
	v_permlane16_swap_b32_e32 v219, v221
	v_lshl_add_u64 v[250:251], v[70:71], 0, v[248:249]
	global_store_dwordx4 v[250:251], v[218:221], off
	v_rcp_f32_e32 v66, v52
	v_add_f32_e32 v52, 1.0, v53
	v_add_f32_e32 v51, 1.0, v51
	v_rcp_f32_e32 v67, v52
	v_mul_f32_e32 v52, 0xbfb8aa3b, v62
	v_rcp_f32_e32 v51, v51
	v_exp_f32_e32 v62, v52
	v_mul_f32_e32 v58, 0xbfb8aa3b, v58
	v_mul_f32_e32 v59, 0xbfb8aa3b, v59
	v_max_f32_e32 v52, 0x38800000, v51
	v_add_f32_e32 v51, 1.0, v62
	v_mul_f32_e32 v62, 0xbfb8aa3b, v63
	v_mul_f32_e32 v63, 0xbfb8aa3b, v64
	v_mul_f32_e32 v64, 0xbfb8aa3b, v65
	v_exp_f32_e32 v58, v58
	v_exp_f32_e32 v59, v59
	v_rcp_f32_e32 v51, v51
	v_exp_f32_e32 v64, v64
	v_add_f32_e32 v58, 1.0, v58
	v_add_f32_e32 v59, 1.0, v59
	v_mul_f32_e32 v54, 0xbfb8aa3b, v54
	v_max_f32_e32 v65, 0x38800000, v51
	v_add_f32_e32 v51, 1.0, v64
	v_rcp_f32_e32 v58, v58
	v_rcp_f32_e32 v59, v59
	v_mul_f32_e32 v60, 0xbfb8aa3b, v60
	v_exp_f32_e32 v54, v54
	v_rcp_f32_e32 v51, v51
	v_exp_f32_e32 v60, v60
	v_max_f32_e32 v53, 0x38800000, v66
	v_max_f32_e32 v66, 0x38800000, v67
	v_max_f32_e32 v67, 0x38800000, v58
	v_max_f32_e32 v58, 0x38800000, v59
	v_mul_f32_e32 v59, 0xbfb8aa3b, v61
	v_add_f32_e32 v54, 1.0, v54
	v_max_f32_e32 v64, 0x38800000, v51
	v_add_f32_e32 v51, 1.0, v60
	v_exp_f32_e32 v59, v59
	v_rcp_f32_e32 v54, v54
	v_mul_f32_e32 v55, 0xbfb8aa3b, v55
	v_rcp_f32_e32 v51, v51
	v_exp_f32_e32 v55, v55
	v_add_f32_e32 v59, 1.0, v59
	v_max_f32_e32 v61, 0x38800000, v54
	v_mul_f32_e32 v54, 0xbfb8aa3b, v56
	v_rcp_f32_e32 v60, v59
	v_max_f32_e32 v59, 0x38800000, v51
	v_add_f32_e32 v51, 1.0, v55
	v_exp_f32_e32 v54, v54
	v_mul_f32_e32 v55, 0xbfb8aa3b, v57
	v_exp_f32_e32 v55, v55
	v_mul_f32_e32 v50, 0xbfb8aa3b, v50
	v_exp_f32_e32 v62, v62
	v_exp_f32_e32 v63, v63
	v_add_f32_e32 v54, 1.0, v54
	v_exp_f32_e32 v50, v50
	v_rcp_f32_e32 v54, v54
	v_add_f32_e32 v55, 1.0, v55
	v_rcp_f32_e32 v55, v55
	v_add_f32_e32 v62, 1.0, v62
	v_add_f32_e32 v63, 1.0, v63
	v_add_f32_e32 v50, 1.0, v50
	v_rcp_f32_e32 v62, v62
	v_rcp_f32_e32 v63, v63
	v_max_f32_e32 v69, 0x38800000, v54
	v_rcp_f32_e32 v54, v50
	v_rcp_f32_e32 v51, v51
	v_max_f32_e32 v70, 0x38800000, v55
	v_rcp_f32_e32 v55, v65
	v_max_f32_e32 v62, 0x38800000, v62
	v_max_f32_e32 v63, 0x38800000, v63
	v_max_f32_e32 v54, 0x38800000, v54
	v_max_f32_e32 v68, 0x38800000, v51
	v_rcp_f32_e32 v50, v62
	v_rcp_f32_e32 v51, v63
	v_fma_mixlo_f16 v54, v54, v55, 0
	v_rcp_f32_e32 v55, v64
	v_max_f32_e32 v60, 0x38800000, v60
	v_pk_mul_f32 v[50:51], v[52:53], v[50:51]
	v_rcp_f32_e32 v56, v58
	v_fma_mixlo_f16 v52, v66, v55, 0
	v_rcp_f32_e32 v66, v67
	v_cvt_pk_f16_f32 v51, v50, v51
	v_pack_b32_f16 v50, v54, v51
	v_alignbit_b32 v51, v52, v51, 16
	v_add_co_u32_e32 v52, vcc, s64, v144
	v_rcp_f32_e32 v57, v59
	s_nop 0
	v_addc_co_u32_e32 v53, vcc, 0, v145, vcc
	s_mov_b32 s5, 0x101000
	v_fma_mixlo_f16 v65, v66, v65, 0
	v_rcp_f32_e32 v66, v60
	v_add_co_u32_e32 v54, vcc, s5, v144
	v_mul_f32_e32 v36, 0xbfb8aa3b, v36
	s_nop 0
	v_addc_co_u32_e32 v55, vcc, 0, v145, vcc
	v_mov_b32_e32 v218, v50
	v_mov_b32_e32 v219, v51
	v_pk_mul_f32 v[50:51], v[56:57], v[62:63]
	v_fma_mixlo_f16 v56, v66, v64, 0
	v_cvt_pk_f16_f32 v51, v50, v51
	v_pack_b32_f16 v50, v65, v51
	v_alignbit_b32 v51, v56, v51, 16
	v_rcp_f32_e32 v56, v68
	v_rcp_f32_e32 v57, v69
	v_rcp_f32_e32 v62, v61
	v_mov_b32_e32 v220, v50
	v_mov_b32_e32 v221, v51
	s_nop 1
	v_permlane16_swap_b32_e32 v218, v220
	v_permlane16_swap_b32_e32 v219, v221
	v_lshl_add_u64 v[250:251], v[54:55], 0, v[248:249]
	global_store_dwordx4 v[250:251], v[218:221], off offset:-4096
	v_rcp_f32_e32 v53, v70
	v_pk_mul_f32 v[50:51], v[58:59], v[56:57]
	v_exp_f32_e32 v36, v36
	v_mul_f32_e32 v37, 0xbfb8aa3b, v37
	v_fma_mixlo_f16 v52, v67, v62, 0
	v_cvt_pk_f16_f32 v51, v50, v51
	v_mul_f32_e32 v35, 0xbfb8aa3b, v35
	v_exp_f32_e32 v37, v37
	v_pack_b32_f16 v50, v52, v51
	v_fma_mixlo_f16 v52, v60, v53, 0
	v_exp_f32_e32 v35, v35
	v_alignbit_b32 v51, v52, v51, 16
	v_mov_b32_e32 v218, v50
	v_mov_b32_e32 v219, v51
	v_cvt_pk_f16_f32 v51, v69, v70
	v_cvt_pk_f16_f32 v50, v61, v68
	v_add_f32_e32 v36, 1.0, v36
	v_mov_b32_e32 v220, v50
	v_mov_b32_e32 v221, v51
	s_nop 1
	v_permlane16_swap_b32_e32 v218, v220
	v_permlane16_swap_b32_e32 v219, v221
	v_lshl_add_u64 v[250:251], v[54:55], 0, v[248:249]
	global_store_dwordx4 v[250:251], v[218:221], off
	v_rcp_f32_e32 v50, v36
	v_add_f32_e32 v36, 1.0, v37
	v_add_f32_e32 v35, 1.0, v35
	v_rcp_f32_e32 v51, v36
	v_mul_f32_e32 v36, 0xbfb8aa3b, v46
	v_rcp_f32_e32 v35, v35
	v_exp_f32_e32 v46, v36
	v_mul_f32_e32 v42, 0xbfb8aa3b, v42
	v_mul_f32_e32 v43, 0xbfb8aa3b, v43
	v_max_f32_e32 v36, 0x38800000, v35
	v_add_f32_e32 v35, 1.0, v46
	v_mul_f32_e32 v46, 0xbfb8aa3b, v47
	v_mul_f32_e32 v47, 0xbfb8aa3b, v48
	v_mul_f32_e32 v48, 0xbfb8aa3b, v49
	v_exp_f32_e32 v42, v42
	v_exp_f32_e32 v43, v43
	v_rcp_f32_e32 v35, v35
	v_exp_f32_e32 v48, v48
	v_add_f32_e32 v42, 1.0, v42
	v_add_f32_e32 v43, 1.0, v43
	v_mul_f32_e32 v38, 0xbfb8aa3b, v38
	v_max_f32_e32 v49, 0x38800000, v35
	v_add_f32_e32 v35, 1.0, v48
; DI float gate_clamped(float x) { return fmaxf(__builtin_amdgcn_rcpf(1.f + __expf(-x)), 6.103515625e-05f); }
;   DI void operator()(const f4 (&acc)[2][2][4][2], const GUnit& u, int wr, int wc, int fr, int fq) const {
;     char* rb = (char*)(gb + (size_t)((u.pm - pm0) * 256 + wr * 64) * 4096 + u.pn * 64 + wc * 16);
;     const unsigned lo = (unsigned)(fr * 4096 + 4 * fq) * 2u;
; #pragma unroll
;     for (int ai = 0; ai < 2; ++ai)
; #pragma unroll
;       for (int m = 0; m < 4; ++m) {
;         f4 gq[4];
; #pragma unroll
;         for (int br = 0; br < 4; ++br)
; #pragma unroll
;           for (int j = 0; j < 4; ++j) gq[br][j] = gate_clamped(acc[ai][br >> 1][m][br & 1][j]);
; #pragma unroll
;         for (int br = 0; br < 4; ++br) {
;           h4 o;
; #pragma unroll
;           for (int j = 0; j < 4; ++j) o[j] = (half_t)(br < 3 ? gq[br][j] * __builtin_amdgcn_rcpf(gq[br + 1][j]) : gq[3][j]);
;           *(h4*)(rb + ((size_t)(ai * 128 + m * 16) * 4096 + br * 1024) * 2 + lo) = o;
;         }
;       }
	v_rcp_f32_e32 v42, v42
	v_rcp_f32_e32 v43, v43
	v_mul_f32_e32 v44, 0xbfb8aa3b, v44
	v_exp_f32_e32 v38, v38
	v_rcp_f32_e32 v35, v35
	v_exp_f32_e32 v44, v44
	v_max_f32_e32 v37, 0x38800000, v50
	v_max_f32_e32 v50, 0x38800000, v51
	v_max_f32_e32 v51, 0x38800000, v42
	v_max_f32_e32 v42, 0x38800000, v43
	v_mul_f32_e32 v43, 0xbfb8aa3b, v45
	v_add_f32_e32 v38, 1.0, v38
	v_max_f32_e32 v48, 0x38800000, v35
	v_add_f32_e32 v35, 1.0, v44
	v_exp_f32_e32 v43, v43
	v_rcp_f32_e32 v38, v38
	v_mul_f32_e32 v39, 0xbfb8aa3b, v39
	v_rcp_f32_e32 v35, v35
	v_exp_f32_e32 v39, v39
	v_add_f32_e32 v43, 1.0, v43
	v_max_f32_e32 v45, 0x38800000, v38
	v_mul_f32_e32 v38, 0xbfb8aa3b, v40
	v_rcp_f32_e32 v44, v43
	v_max_f32_e32 v43, 0x38800000, v35
	v_add_f32_e32 v35, 1.0, v39
	v_exp_f32_e32 v38, v38
	v_mul_f32_e32 v39, 0xbfb8aa3b, v41
	v_exp_f32_e32 v39, v39
	v_mul_f32_e32 v34, 0xbfb8aa3b, v34
	v_exp_f32_e32 v46, v46
	v_exp_f32_e32 v47, v47
	v_add_f32_e32 v38, 1.0, v38
	v_exp_f32_e32 v34, v34
	v_rcp_f32_e32 v38, v38
	v_add_f32_e32 v39, 1.0, v39
	v_rcp_f32_e32 v39, v39
	v_add_f32_e32 v46, 1.0, v46
	v_add_f32_e32 v47, 1.0, v47
	v_add_f32_e32 v34, 1.0, v34
	v_rcp_f32_e32 v46, v46
	v_rcp_f32_e32 v47, v47
	v_max_f32_e32 v53, 0x38800000, v38
	v_rcp_f32_e32 v38, v34
	v_rcp_f32_e32 v35, v35
	v_max_f32_e32 v54, 0x38800000, v39
	v_rcp_f32_e32 v39, v49
	v_max_f32_e32 v46, 0x38800000, v46
	v_max_f32_e32 v47, 0x38800000, v47
	v_max_f32_e32 v38, 0x38800000, v38
	v_max_f32_e32 v52, 0x38800000, v35
	v_rcp_f32_e32 v34, v46
	v_rcp_f32_e32 v35, v47
	v_fma_mixlo_f16 v38, v38, v39, 0
	v_rcp_f32_e32 v39, v48
	v_max_f32_e32 v44, 0x38800000, v44
	v_pk_mul_f32 v[34:35], v[36:37], v[34:35]
	v_rcp_f32_e32 v40, v42
	v_fma_mixlo_f16 v36, v50, v39, 0
	v_rcp_f32_e32 v50, v51
	v_cvt_pk_f16_f32 v35, v34, v35
	v_pack_b32_f16 v34, v38, v35
	v_alignbit_b32 v35, v36, v35, 16
	v_add_co_u32_e32 v36, vcc, s67, v144
	v_rcp_f32_e32 v41, v43
	s_nop 0
	v_addc_co_u32_e32 v37, vcc, 0, v145, vcc
	s_mov_b32 s5, 0x121000
	v_fma_mixlo_f16 v49, v50, v49, 0
	v_rcp_f32_e32 v50, v44
	v_add_co_u32_e32 v38, vcc, s5, v144
	v_mul_f32_e32 v20, 0xbfb8aa3b, v20
	s_nop 0
	v_addc_co_u32_e32 v39, vcc, 0, v145, vcc
	v_mov_b32_e32 v218, v34
	v_mov_b32_e32 v219, v35
	v_pk_mul_f32 v[34:35], v[40:41], v[46:47]
	v_fma_mixlo_f16 v40, v50, v48, 0
	v_cvt_pk_f16_f32 v35, v34, v35
	v_pack_b32_f16 v34, v49, v35
	v_alignbit_b32 v35, v40, v35, 16
	v_rcp_f32_e32 v40, v52
	v_rcp_f32_e32 v41, v53
	v_rcp_f32_e32 v46, v45
	v_mov_b32_e32 v220, v34
	v_mov_b32_e32 v221, v35
	s_nop 1
	v_permlane16_swap_b32_e32 v218, v220
	v_permlane16_swap_b32_e32 v219, v221
	v_lshl_add_u64 v[250:251], v[38:39], 0, v[248:249]
	global_store_dwordx4 v[250:251], v[218:221], off offset:-4096
	v_rcp_f32_e32 v37, v54
	v_pk_mul_f32 v[34:35], v[42:43], v[40:41]
	v_exp_f32_e32 v20, v20
	v_mul_f32_e32 v21, 0xbfb8aa3b, v21
	v_fma_mixlo_f16 v36, v51, v46, 0
	v_cvt_pk_f16_f32 v35, v34, v35
	v_mul_f32_e32 v19, 0xbfb8aa3b, v19
	v_exp_f32_e32 v21, v21
	v_pack_b32_f16 v34, v36, v35
	v_fma_mixlo_f16 v36, v44, v37, 0
	v_exp_f32_e32 v19, v19
	v_alignbit_b32 v35, v36, v35, 16
	v_mov_b32_e32 v218, v34
	v_mov_b32_e32 v219, v35
	v_cvt_pk_f16_f32 v35, v53, v54
	v_cvt_pk_f16_f32 v34, v45, v52
	v_add_f32_e32 v20, 1.0, v20
	v_mov_b32_e32 v220, v34
	v_mov_b32_e32 v221, v35
	s_nop 1
	v_permlane16_swap_b32_e32 v218, v220
	v_permlane16_swap_b32_e32 v219, v221
	v_lshl_add_u64 v[250:251], v[38:39], 0, v[248:249]
	global_store_dwordx4 v[250:251], v[218:221], off
	v_rcp_f32_e32 v34, v20
	v_add_f32_e32 v20, 1.0, v21
	v_add_f32_e32 v19, 1.0, v19
	v_rcp_f32_e32 v35, v20
	v_mul_f32_e32 v20, 0xbfb8aa3b, v30
	v_rcp_f32_e32 v19, v19
	v_exp_f32_e32 v30, v20
	v_mul_f32_e32 v26, 0xbfb8aa3b, v26
	v_mul_f32_e32 v27, 0xbfb8aa3b, v27
	v_max_f32_e32 v20, 0x38800000, v19
	v_add_f32_e32 v19, 1.0, v30
	v_mul_f32_e32 v30, 0xbfb8aa3b, v31
	v_mul_f32_e32 v31, 0xbfb8aa3b, v32
	v_mul_f32_e32 v32, 0xbfb8aa3b, v33
	v_exp_f32_e32 v26, v26
	v_exp_f32_e32 v27, v27
	v_rcp_f32_e32 v19, v19
	v_exp_f32_e32 v32, v32
	v_add_f32_e32 v26, 1.0, v26
	v_add_f32_e32 v27, 1.0, v27
	v_mul_f32_e32 v22, 0xbfb8aa3b, v22
	v_max_f32_e32 v33, 0x38800000, v19
	v_add_f32_e32 v19, 1.0, v32
	v_rcp_f32_e32 v26, v26
	v_rcp_f32_e32 v27, v27
	v_mul_f32_e32 v28, 0xbfb8aa3b, v28
	v_exp_f32_e32 v22, v22
	v_rcp_f32_e32 v19, v19
	v_exp_f32_e32 v28, v28
	v_max_f32_e32 v21, 0x38800000, v34
	v_max_f32_e32 v34, 0x38800000, v35
	v_max_f32_e32 v35, 0x38800000, v26
	v_max_f32_e32 v26, 0x38800000, v27
	v_mul_f32_e32 v27, 0xbfb8aa3b, v29
	v_add_f32_e32 v22, 1.0, v22
	v_max_f32_e32 v32, 0x38800000, v19
	v_add_f32_e32 v19, 1.0, v28
	v_exp_f32_e32 v27, v27
	v_rcp_f32_e32 v22, v22
	v_mul_f32_e32 v23, 0xbfb8aa3b, v23
	v_rcp_f32_e32 v19, v19
	v_exp_f32_e32 v23, v23
	v_add_f32_e32 v27, 1.0, v27
	v_max_f32_e32 v29, 0x38800000, v22
	v_mul_f32_e32 v22, 0xbfb8aa3b, v24
	v_rcp_f32_e32 v28, v27
	v_max_f32_e32 v27, 0x38800000, v19
	v_add_f32_e32 v19, 1.0, v23
	v_exp_f32_e32 v22, v22
	v_mul_f32_e32 v23, 0xbfb8aa3b, v25
	v_exp_f32_e32 v23, v23
	v_mul_f32_e32 v18, 0xbfb8aa3b, v18
	v_exp_f32_e32 v30, v30
	v_exp_f32_e32 v31, v31
	v_add_f32_e32 v22, 1.0, v22
	v_exp_f32_e32 v18, v18
	v_rcp_f32_e32 v22, v22
	v_add_f32_e32 v23, 1.0, v23
	v_rcp_f32_e32 v23, v23
	v_add_f32_e32 v30, 1.0, v30
	v_add_f32_e32 v31, 1.0, v31
	v_add_f32_e32 v18, 1.0, v18
	v_rcp_f32_e32 v30, v30
	v_rcp_f32_e32 v31, v31
	v_max_f32_e32 v37, 0x38800000, v22
	v_rcp_f32_e32 v22, v18
	v_rcp_f32_e32 v19, v19
	v_max_f32_e32 v38, 0x38800000, v23
	v_rcp_f32_e32 v23, v33
	v_max_f32_e32 v30, 0x38800000, v30
	v_max_f32_e32 v31, 0x38800000, v31
	v_max_f32_e32 v22, 0x38800000, v22
	v_max_f32_e32 v36, 0x38800000, v19
	v_rcp_f32_e32 v18, v30
; DI float gate_clamped(float x) { return fmaxf(__builtin_amdgcn_rcpf(1.f + __expf(-x)), 6.103515625e-05f); }
;   DI void operator()(const f4 (&acc)[2][2][4][2], const GUnit& u, int wr, int wc, int fr, int fq) const {
;     char* rb = (char*)(gb + (size_t)((u.pm - pm0) * 256 + wr * 64) * 4096 + u.pn * 64 + wc * 16);
;     const unsigned lo = (unsigned)(fr * 4096 + 4 * fq) * 2u;
; #pragma unroll
;     for (int ai = 0; ai < 2; ++ai)
; #pragma unroll
;       for (int m = 0; m < 4; ++m) {
;         f4 gq[4];
; #pragma unroll
;         for (int br = 0; br < 4; ++br)
; #pragma unroll
;           for (int j = 0; j < 4; ++j) gq[br][j] = gate_clamped(acc[ai][br >> 1][m][br & 1][j]);
; #pragma unroll
;         for (int br = 0; br < 4; ++br) {
;           h4 o;
; #pragma unroll
;           for (int j = 0; j < 4; ++j) o[j] = (half_t)(br < 3 ? gq[br][j] * __builtin_amdgcn_rcpf(gq[br + 1][j]) : gq[3][j]);
;           *(h4*)(rb + ((size_t)(ai * 128 + m * 16) * 4096 + br * 1024) * 2 + lo) = o;
;         }
;       }
	v_rcp_f32_e32 v19, v31
	v_fma_mixlo_f16 v22, v22, v23, 0
	v_rcp_f32_e32 v23, v32
	v_max_f32_e32 v28, 0x38800000, v28
	v_pk_mul_f32 v[18:19], v[20:21], v[18:19]
	v_rcp_f32_e32 v24, v26
	v_fma_mixlo_f16 v20, v34, v23, 0
	v_rcp_f32_e32 v34, v35
	v_cvt_pk_f16_f32 v19, v18, v19
	v_pack_b32_f16 v18, v22, v19
	v_alignbit_b32 v19, v20, v19, 16
	v_add_co_u32_e32 v20, vcc, s48, v144
	v_rcp_f32_e32 v25, v27
	s_nop 0
	v_addc_co_u32_e32 v21, vcc, 0, v145, vcc
	s_mov_b32 s5, 0x141000
	v_fma_mixlo_f16 v33, v34, v33, 0
	v_rcp_f32_e32 v34, v28
	v_add_co_u32_e32 v22, vcc, s5, v144
	v_mul_f32_e32 v4, 0xbfb8aa3b, v4
	s_nop 0
	v_addc_co_u32_e32 v23, vcc, 0, v145, vcc
	v_mov_b32_e32 v218, v18
	v_mov_b32_e32 v219, v19
	v_pk_mul_f32 v[18:19], v[24:25], v[30:31]
	v_fma_mixlo_f16 v24, v34, v32, 0
	v_cvt_pk_f16_f32 v19, v18, v19
	v_pack_b32_f16 v18, v33, v19
	v_alignbit_b32 v19, v24, v19, 16
	v_rcp_f32_e32 v24, v36
	v_rcp_f32_e32 v25, v37
	v_rcp_f32_e32 v30, v29
	v_mov_b32_e32 v220, v18
	v_mov_b32_e32 v221, v19
	s_nop 1
	v_permlane16_swap_b32_e32 v218, v220
	v_permlane16_swap_b32_e32 v219, v221
	v_lshl_add_u64 v[250:251], v[22:23], 0, v[248:249]
	global_store_dwordx4 v[250:251], v[218:221], off offset:-4096
	v_rcp_f32_e32 v21, v38
	v_pk_mul_f32 v[18:19], v[26:27], v[24:25]
	v_exp_f32_e32 v4, v4
	v_mul_f32_e32 v5, 0xbfb8aa3b, v5
	v_fma_mixlo_f16 v20, v35, v30, 0
	v_cvt_pk_f16_f32 v19, v18, v19
	v_mul_f32_e32 v3, 0xbfb8aa3b, v3
	v_exp_f32_e32 v5, v5
	v_pack_b32_f16 v18, v20, v19
	v_fma_mixlo_f16 v20, v28, v21, 0
	v_exp_f32_e32 v3, v3
	v_alignbit_b32 v19, v20, v19, 16
	v_mov_b32_e32 v218, v18
	v_mov_b32_e32 v219, v19
	v_cvt_pk_f16_f32 v19, v37, v38
	v_cvt_pk_f16_f32 v18, v29, v36
	v_add_f32_e32 v4, 1.0, v4
	v_mov_b32_e32 v220, v18
	v_mov_b32_e32 v221, v19
	s_nop 1
	v_permlane16_swap_b32_e32 v218, v220
	v_permlane16_swap_b32_e32 v219, v221
	v_lshl_add_u64 v[250:251], v[22:23], 0, v[248:249]
	global_store_dwordx4 v[250:251], v[218:221], off
	v_rcp_f32_e32 v18, v4
	v_add_f32_e32 v4, 1.0, v5
	v_add_f32_e32 v3, 1.0, v3
	v_rcp_f32_e32 v19, v4
	v_mul_f32_e32 v4, 0xbfb8aa3b, v14
	v_rcp_f32_e32 v3, v3
	v_exp_f32_e32 v14, v4
	v_mul_f32_e32 v10, 0xbfb8aa3b, v10
	v_mul_f32_e32 v11, 0xbfb8aa3b, v11
	v_max_f32_e32 v4, 0x38800000, v3
	v_add_f32_e32 v3, 1.0, v14
	v_mul_f32_e32 v14, 0xbfb8aa3b, v15
	v_mul_f32_e32 v15, 0xbfb8aa3b, v16
	v_mul_f32_e32 v16, 0xbfb8aa3b, v17
	v_exp_f32_e32 v10, v10
	v_exp_f32_e32 v11, v11
	v_rcp_f32_e32 v3, v3
	v_exp_f32_e32 v16, v16
	v_add_f32_e32 v10, 1.0, v10
	v_add_f32_e32 v11, 1.0, v11
	v_mul_f32_e32 v6, 0xbfb8aa3b, v6
	v_max_f32_e32 v17, 0x38800000, v3
	v_add_f32_e32 v3, 1.0, v16
	v_rcp_f32_e32 v10, v10
	v_rcp_f32_e32 v11, v11
	v_mul_f32_e32 v12, 0xbfb8aa3b, v12
	v_exp_f32_e32 v6, v6
	v_rcp_f32_e32 v3, v3
	v_exp_f32_e32 v12, v12
	v_max_f32_e32 v5, 0x38800000, v18
	v_max_f32_e32 v18, 0x38800000, v19
	v_max_f32_e32 v19, 0x38800000, v10
	v_max_f32_e32 v10, 0x38800000, v11
	v_mul_f32_e32 v11, 0xbfb8aa3b, v13
	v_add_f32_e32 v6, 1.0, v6
	v_max_f32_e32 v16, 0x38800000, v3
	v_add_f32_e32 v3, 1.0, v12
	v_exp_f32_e32 v11, v11
	v_rcp_f32_e32 v6, v6
	v_mul_f32_e32 v7, 0xbfb8aa3b, v7
	v_rcp_f32_e32 v3, v3
	v_exp_f32_e32 v7, v7
	v_add_f32_e32 v11, 1.0, v11
	v_max_f32_e32 v13, 0x38800000, v6
	v_mul_f32_e32 v6, 0xbfb8aa3b, v8
	v_rcp_f32_e32 v12, v11
	v_max_f32_e32 v11, 0x38800000, v3
	v_add_f32_e32 v3, 1.0, v7
	v_exp_f32_e32 v6, v6
	v_mul_f32_e32 v7, 0xbfb8aa3b, v9
	v_exp_f32_e32 v7, v7
	v_mul_f32_e32 v2, 0xbfb8aa3b, v2
	v_exp_f32_e32 v14, v14
	v_exp_f32_e32 v15, v15
	v_add_f32_e32 v6, 1.0, v6
	v_exp_f32_e32 v2, v2
	v_rcp_f32_e32 v6, v6
	v_add_f32_e32 v7, 1.0, v7
	v_rcp_f32_e32 v7, v7
	v_add_f32_e32 v14, 1.0, v14
	v_add_f32_e32 v15, 1.0, v15
	v_add_f32_e32 v2, 1.0, v2
	v_rcp_f32_e32 v14, v14
	v_rcp_f32_e32 v15, v15
	v_max_f32_e32 v9, 0x38800000, v6
	v_rcp_f32_e32 v6, v2
	v_rcp_f32_e32 v3, v3
	v_max_f32_e32 v20, 0x38800000, v7
	v_rcp_f32_e32 v7, v17
	v_max_f32_e32 v14, 0x38800000, v14
	v_max_f32_e32 v15, 0x38800000, v15
	v_max_f32_e32 v6, 0x38800000, v6
	v_max_f32_e32 v8, 0x38800000, v3
	v_rcp_f32_e32 v2, v14
	v_rcp_f32_e32 v3, v15
	v_fma_mixlo_f16 v6, v6, v7, 0
	v_rcp_f32_e32 v7, v16
	v_max_f32_e32 v12, 0x38800000, v12
	v_pk_mul_f32 v[2:3], v[4:5], v[2:3]
	s_mov_b32 s84, s66
	v_fma_mixlo_f16 v4, v18, v7, 0
	v_rcp_f32_e32 v18, v19
	v_cvt_pk_f16_f32 v3, v2, v3
	v_pack_b32_f16 v2, v6, v3
	v_rcp_f32_e32 v6, v10
	v_rcp_f32_e32 v7, v11
	v_fma_mixlo_f16 v17, v18, v17, 0
	v_rcp_f32_e32 v18, v12
	v_alignbit_b32 v3, v4, v3, 16
	v_add_co_u32_e32 v4, vcc, s49, v144
	s_mov_b32 s10, s4
	s_nop 0
	v_addc_co_u32_e32 v5, vcc, 0, v145, vcc
	v_mov_b32_e32 v218, v2
	v_mov_b32_e32 v219, v3
	v_pk_mul_f32 v[2:3], v[6:7], v[14:15]
	v_fma_mixlo_f16 v6, v18, v16, 0
	v_cvt_pk_f16_f32 v3, v2, v3
	v_pack_b32_f16 v2, v17, v3
	v_alignbit_b32 v3, v6, v3, 16
	v_rcp_f32_e32 v6, v8
	v_rcp_f32_e32 v7, v9
	v_rcp_f32_e32 v14, v13
	v_mov_b32_e32 v220, v2
	v_mov_b32_e32 v221, v3
	s_nop 1
	v_permlane16_swap_b32_e32 v218, v220
	v_permlane16_swap_b32_e32 v219, v221
	v_lshl_add_u64 v[250:251], v[4:5], 0, v[248:249]
	global_store_dwordx4 v[250:251], v[218:221], off
	v_rcp_f32_e32 v5, v20
	v_pk_mul_f32 v[2:3], v[10:11], v[6:7]
	v_fma_mixlo_f16 v4, v19, v14, 0
	v_cvt_pk_f16_f32 v3, v2, v3
	v_pack_b32_f16 v2, v4, v3
	v_fma_mixlo_f16 v4, v12, v5, 0
	v_alignbit_b32 v3, v4, v3, 16
	v_add_co_u32_e32 v4, vcc, 0x161000, v144
	s_mov_b64 s[14:15], s[8:9]
	s_nop 0
	v_addc_co_u32_e32 v5, vcc, 0, v145, vcc
	v_mov_b32_e32 v218, v2
	v_mov_b32_e32 v219, v3
	v_cvt_pk_f16_f32 v3, v9, v20
	v_cvt_pk_f16_f32 v2, v13, v8
	s_and_b64 vcc, exec, s[2:3]
	s_mov_b64 s[12:13], s[6:7]
	v_mov_b32_e32 v220, v2
	v_mov_b32_e32 v221, v3
	s_nop 1
	v_permlane16_swap_b32_e32 v218, v220
	v_permlane16_swap_b32_e32 v219, v221
	v_lshl_add_u64 v[250:251], v[4:5], 0, v[248:249]
	global_store_dwordx4 v[250:251], v[218:221], off
	s_cbranch_vccnz .LBB0_2282
